# combo2 + XCD leader invalidate hoisted behind its write-back
# baseline (speedup 1.0000x reference)
.LBB0_76:
	s_andn2_saveexec_b64 s[12:13], s[12:13]
	s_cbranch_execz .LBB0_96
	s_mov_b64 s[12:13], exec
	buffer_wbl2 sc1
	s_waitcnt lgkmcnt(0)
	s_waitcnt vmcnt(0)
	buffer_inv sc1
	v_mbcnt_lo_u32_b32 v1, s12, 0
	v_mbcnt_hi_u32_b32 v1, s13, v1
	v_cmp_eq_u32_e32 vcc, 0, v1
	s_and_saveexec_b64 s[18:19], vcc
	s_cbranch_execz .LBB0_79
	s_bcnt1_i32_b64 s12, s[12:13]
	v_mov_b32_e32 v2, 0x22207000
	v_mov_b32_e32 v3, s12
	global_atomic_add v2, v2, v3, s[24:25] offset:1280 sc0

.LBB0_93:
	s_or_b64 exec, exec, s[12:13]
	s_mov_b64 s[12:13], exec
	v_mbcnt_lo_u32_b32 v0, s12, 0
	v_mbcnt_hi_u32_b32 v0, s13, v0
	v_cmp_eq_u32_e32 vcc, 0, v0
	s_waitcnt vmcnt(0)

	s_and_saveexec_b64 s[18:19], vcc
	s_cbranch_execz .LBB0_95
	s_bcnt1_i32_b64 s12, s[12:13]
	v_mov_b32_e32 v0, 0x2000
	v_mov_b32_e32 v1, s12
	global_atomic_add v0, v1, s[4:5] offset:1024

.LBB0_174:
	s_andn2_saveexec_b64 s[8:9], s[8:9]
	s_cbranch_execz .LBB0_194
	s_mov_b64 s[8:9], exec
	buffer_wbl2 sc1
	s_waitcnt lgkmcnt(0)
	s_waitcnt vmcnt(0)
	buffer_inv sc1
	v_mbcnt_lo_u32_b32 v1, s8, 0
	v_mbcnt_hi_u32_b32 v1, s9, v1
	v_cmp_eq_u32_e32 vcc, 0, v1
	s_and_saveexec_b64 s[30:31], vcc
	s_cbranch_execz .LBB0_177
	s_bcnt1_i32_b64 s8, s[8:9]
	v_mov_b32_e32 v2, 0x22207000
	v_mov_b32_e32 v3, s8
	global_atomic_add v2, v2, v3, s[24:25] offset:1280 sc0

.LBB0_191:
	s_or_b64 exec, exec, s[8:9]
	s_mov_b64 s[8:9], exec
	v_mbcnt_lo_u32_b32 v0, s8, 0
	v_mbcnt_hi_u32_b32 v0, s9, v0
	v_cmp_eq_u32_e32 vcc, 0, v0
	s_waitcnt vmcnt(0)

	s_and_saveexec_b64 s[30:31], vcc
	s_cbranch_execz .LBB0_193
	s_bcnt1_i32_b64 s8, s[8:9]
	v_mov_b32_e32 v0, 0x2000
	v_mov_b32_e32 v1, s8
	global_atomic_add v0, v1, s[4:5] offset:1024

.LBB0_606:
	s_andn2_saveexec_b64 s[8:9], s[8:9]
	s_cbranch_execz .LBB0_626
	s_mov_b64 s[8:9], exec
	buffer_wbl2 sc1
	s_waitcnt lgkmcnt(0)
	s_waitcnt vmcnt(0)
	buffer_inv sc1
	v_mbcnt_lo_u32_b32 v1, s8, 0
	v_mbcnt_hi_u32_b32 v1, s9, v1
	v_cmp_eq_u32_e32 vcc, 0, v1
	s_and_saveexec_b64 s[10:11], vcc
	s_cbranch_execz .LBB0_609
	s_bcnt1_i32_b64 s8, s[8:9]
	v_mov_b32_e32 v2, 0x22207000
	v_mov_b32_e32 v3, s8
	global_atomic_add v2, v2, v3, s[24:25] offset:1280 sc0

.LBB0_623:
	s_or_b64 exec, exec, s[8:9]
	s_mov_b64 s[8:9], exec
	v_mbcnt_lo_u32_b32 v0, s8, 0
	v_mbcnt_hi_u32_b32 v0, s9, v0
	v_cmp_eq_u32_e32 vcc, 0, v0
	s_waitcnt vmcnt(0)

	s_and_saveexec_b64 s[10:11], vcc
	s_cbranch_execz .LBB0_625
	s_bcnt1_i32_b64 s8, s[8:9]
	v_mov_b32_e32 v0, 0x2000
	v_mov_b32_e32 v1, s8
	global_atomic_add v0, v1, s[4:5] offset:1024

.LBB0_877:
	s_andn2_saveexec_b64 s[8:9], s[8:9]
	s_cbranch_execz .LBB0_897
	s_mov_b64 s[8:9], exec
	buffer_wbl2 sc1
	s_waitcnt lgkmcnt(0)
	s_waitcnt vmcnt(0)
	buffer_inv sc1
	v_mbcnt_lo_u32_b32 v1, s8, 0
	v_mbcnt_hi_u32_b32 v1, s9, v1
	v_cmp_eq_u32_e32 vcc, 0, v1
	s_and_saveexec_b64 s[10:11], vcc
	s_cbranch_execz .LBB0_880
	s_bcnt1_i32_b64 s7, s[8:9]
	v_mov_b32_e32 v2, 0x22207000
	v_mov_b32_e32 v3, s7
	global_atomic_add v2, v2, v3, s[24:25] offset:1280 sc0

.LBB0_894:
	s_or_b64 exec, exec, s[8:9]
	s_mov_b64 s[8:9], exec
	v_mbcnt_lo_u32_b32 v0, s8, 0
	v_mbcnt_hi_u32_b32 v0, s9, v0
	v_cmp_eq_u32_e32 vcc, 0, v0
	s_waitcnt vmcnt(0)

	s_and_saveexec_b64 s[10:11], vcc
	s_cbranch_execz .LBB0_896
	s_bcnt1_i32_b64 s7, s[8:9]
	v_mov_b32_e32 v0, 0x2000
	v_mov_b32_e32 v1, s7
	global_atomic_add v0, v1, s[4:5] offset:1024

.LBB0_1497:
	s_andn2_saveexec_b64 s[4:5], s[4:5]
	s_cbranch_execz .LBB0_1517
	s_mov_b64 s[4:5], exec
	buffer_wbl2 sc1
	s_waitcnt lgkmcnt(0)
	s_waitcnt vmcnt(0)
	buffer_inv sc1
	v_mbcnt_lo_u32_b32 v1, s4, 0
	v_mbcnt_hi_u32_b32 v1, s5, v1
	v_cmp_eq_u32_e32 vcc, 0, v1
	s_and_saveexec_b64 s[6:7], vcc
	s_cbranch_execz .LBB0_1500
	s_bcnt1_i32_b64 s4, s[4:5]
	v_mov_b32_e32 v2, 0x22207000
	v_mov_b32_e32 v3, s4
	global_atomic_add v2, v2, v3, s[24:25] offset:1280 sc0

.LBB0_1514:
	s_or_b64 exec, exec, s[4:5]
	s_mov_b64 s[4:5], exec
	v_mbcnt_lo_u32_b32 v0, s4, 0
	v_mbcnt_hi_u32_b32 v0, s5, v0
	v_cmp_eq_u32_e32 vcc, 0, v0
	s_waitcnt vmcnt(0)

	s_and_saveexec_b64 s[6:7], vcc
	s_cbranch_execz .LBB0_1516
	s_bcnt1_i32_b64 s4, s[4:5]
	v_mov_b32_e32 v0, 0x2000
	v_mov_b32_e32 v1, s4
	global_atomic_add v0, v1, s[2:3] offset:1024
